# attention item prologue: first V^T tile load issued together with first K tile load
# speedup vs baseline: 1.0039x; 1.0039x over previous
; DI f32x16 zero16() { f32x16 z; for (int i = 0; i < 16; ++i) z[i] = 0.f; return z; }
; DI void attn_item(const Params& p, char* lds, int item) {
;     ...
;   const size_t q0 = (size_t)b * SEQ + qc * 64 + qt * 32;
;   bf16x8 Qf[4];
; #pragma unroll
;   for (int kk = 0; kk < 4; ++kk) Qf[kk] = ldfrag(PA + (q0 + l31) * 1024 + h * 64 + kk * 16 + 8 * hh);
;   const int kcs = (c0 >= 8) ? c0 - 8 : 0, kce = c0 + 3;
;   *(uint4*)(Kl + sr * 72 + sc8) = *(const uint4*)(kg + (size_t)(kcs * 64) * 1024);
;   *(uint4*)(Vl + sr * 72 + sc8) = *(const uint4*)(vg + kcs * 64);
;   __syncthreads();
;   f32x16 O[2]; O[0] = zero16(); O[1] = zero16();
;   float mrun = -INFINITY, lrun = 0.f;
.LBB0_393:
	s_or_b64 exec, exec, s[0:1]
	s_bfe_u32 s1, s15, 0x50002
	s_lshl_b32 s0, s1, 2
	s_min_u32 s0, s0, 8
	v_lshrrev_b32_e32 v11, 1, v2
	v_lshlrev_b32_e32 v4, 1, v2
	s_lshl_b32 s1, s1, 8
	s_lshl_b32 s16, s0, 6
	v_and_b32_e32 v0, 19, v2
	v_and_b32_e32 v3, 4, v11
	v_and_b32_e32 v4, 8, v4
	s_lshl_b32 s23, s6, 6
	s_sub_i32 s22, s1, s16
	v_or3_b32 v12, v0, v3, v4
	v_ashrrev_i32_e32 v4, 3, v2
	s_add_i32 s16, s23, s13
	v_and_b32_e32 v8, 31, v2
	v_bfe_u32 v9, v2, 5, 1
	v_ashrrev_i32_e32 v10, 7, v2
	v_lshlrev_b32_e32 v0, 4, v2
	v_add_u32_e32 v2, s16, v4
	s_lshl_b32 s1, s75, 2
	v_ashrrev_i32_e32 v3, 31, v2
	s_and_b32 s1, s1, 0x7c
	v_lshlrev_b64 v[2:3], 14, v[2:3]
	v_add_u32_e32 v81, s1, v10
	v_and_b32_e32 v0, 0x70, v0
	v_lshl_add_u64 v[2:3], s[10:11], 0, v[2:3]
	v_lshl_add_u64 v[86:87], v[2:3], 0, v[0:1]
	v_lshlrev_b32_e32 v2, 6, v81
	v_ashrrev_i32_e32 v5, 31, v4
	v_ashrrev_i32_e32 v3, 31, v2
	v_lshl_add_u64 v[6:7], v[4:5], 0, s[4:5]
	v_readlane_b32 s18, v250, 8
	v_lshl_add_u64 v[2:3], v[2:3], 0, s[4:5]
	v_and_b32_e32 v11, 32, v11
	v_lshlrev_b64 v[6:7], 11, v[6:7]
	v_readlane_b32 s19, v250, 9
	v_or3_b32 v2, v2, v11, v8
	s_lshl_b32 s6, s6, 7
	v_lshl_add_u64 v[6:7], s[18:19], 0, v[6:7]
	v_lshlrev_b64 v[84:85], 11, v[2:3]
	v_lshl_add_u64 v[6:7], v[6:7], 0, s[6:7]
	v_lshl_add_u64 v[2:3], s[18:19], 0, v[84:85]
	v_lshl_add_u64 v[82:83], v[6:7], 0, v[0:1]
	v_lshl_add_u64 v[2:3], v[2:3], 0, s[6:7]
	v_lshlrev_b32_e32 v6, 4, v9
	v_mov_b32_e32 v7, v1
	v_lshl_add_u64 v[2:3], v[2:3], 0, v[6:7]
	v_sub_u32_e64 v7, s1, 8 clamp
	global_load_dwordx4 v[64:67], v[2:3], off
	global_load_dwordx4 v[68:71], v[2:3], off offset:32
	global_load_dwordx4 v[72:75], v[2:3], off offset:64
	global_load_dwordx4 v[76:79], v[2:3], off offset:96
	v_lshlrev_b32_e32 v2, 17, v7
	v_mov_b32_e32 v3, v1
	v_lshl_add_u64 v[2:3], v[82:83], 0, v[2:3]
	v_mul_lo_u32 v4, v4, s34
	v_add3_u32 v131, 0, v4, v0
	global_load_dwordx4 v[2:5], v[2:3], off offset:1024
	v_lshlrev_b32_e32 v0, 7, v7
	v_lshl_add_u64 v[144:145], v[86:87], 0, v[0:1]
	global_load_dwordx4 v[140:143], v[144:145], off
	v_lshlrev_b32_e32 v80, 3, v9
	v_mov_b32_e32 v14, v1
	v_mov_b32_e32 v15, v1
	v_readfirstlane_b32 s26, v7
	v_mov_b32_e32 v7, v1
	v_mov_b32_e32 v9, v1
	v_mov_b32_e32 v13, v1
	s_or_b32 s27, s1, 3
	v_add_u32_e32 v132, -8, v81
	s_mov_b32 s76, 0
	v_mov_b32_e32 v138, 0xff800000
	v_mov_b32_e32 v137, 0
	s_waitcnt vmcnt(1)
	ds_write_b128 v131, v[2:5]
	v_add_u32_e32 v0, 0, v6
	v_mad_u32_u24 v133, v8, s34, v0
	v_mad_u32_u24 v134, v12, s34, v0
	v_sub_u32_e32 v0, v80, v8
	v_sub_u32_e32 v0, v0, v11
	v_mov_b32_e32 v6, v1
	v_mov_b32_e32 v8, v1
	v_mov_b32_e32 v12, v1
	s_waitcnt vmcnt(0)
	ds_write_b128 v131, v[140:143] offset:18432
	v_add_lshl_u32 v2, v10, s0, 6
	v_sub_u32_e32 v135, v0, v2
	v_or_b32_e32 v0, v11, v2
	v_sub_u32_e32 v136, 0, v0
	v_mov_b32_e32 v0, v1
	v_mov_b32_e32 v2, v1
	v_mov_b32_e32 v3, v1
	v_mov_b32_e32 v4, v1
	v_mov_b32_e32 v5, v1
	v_mov_b32_e32 v10, v1
	v_mov_b32_e32 v11, v1
	v_mov_b64_e32 v[30:31], v[14:15]
	v_mov_b64_e32 v[46:47], v[14:15]
	v_mov_b64_e32 v[28:29], v[12:13]
	v_mov_b64_e32 v[26:27], v[10:11]
	v_mov_b64_e32 v[24:25], v[8:9]
	v_mov_b64_e32 v[22:23], v[6:7]
	v_mov_b64_e32 v[20:21], v[4:5]
	v_mov_b64_e32 v[18:19], v[2:3]
	v_mov_b64_e32 v[16:17], v[0:1]
	v_mov_b64_e32 v[44:45], v[12:13]
	v_mov_b64_e32 v[42:43], v[10:11]
	v_mov_b64_e32 v[40:41], v[8:9]
	v_mov_b64_e32 v[38:39], v[6:7]
	v_mov_b64_e32 v[36:37], v[4:5]
	v_mov_b64_e32 v[34:35], v[2:3]
	v_mov_b64_e32 v[32:33], v[0:1]
	s_waitcnt lgkmcnt(0)
	s_barrier
	s_branch .LBB0_395
